# v19
# speedup vs baseline: 1.0054x; 1.0054x over previous
; __device__ __forceinline__ unsigned xb_add(unsigned* p, unsigned v) { return __hip_atomic_fetch_add(p, v, __ATOMIC_RELAXED, __HIP_MEMORY_SCOPE_AGENT); }
; __device__ __forceinline__ void xcd_barrier(const XcdBarrier& b) {
;     asm volatile("s_waitcnt vmcnt(0)" ::: "memory");
;     __syncthreads();
;     if (threadIdx.x == 0) {
;         unsigned* bar = b.bar;
;         __builtin_amdgcn_s_waitcnt(0);
;         unsigned nloc = b.st[0], nx = b.st[1];
;         if (nloc == 0u) { xcd_barrier_complete(bar, b.x, nloc, nx); b.st[0] = nloc; b.st[1] = nx; }
;         const unsigned old = xb_add(&bar[XB_XSUB(b.x)], 1u);
.LBB0_325:
	s_mov_b32 s10, 0
	s_getreg_b32 s12, hwreg(HW_REG_XCC_ID, 0, 4)
	s_waitcnt vmcnt(0)
	s_waitcnt vmcnt(0)
	s_barrier
	s_and_saveexec_b64 s[6:7], s[4:5]
	s_cbranch_execz .LBB0_377
	v_writelane_b32 v16, s14, 0
	v_writelane_b32 v16, s15, 1
	v_writelane_b32 v16, s16, 2
	v_writelane_b32 v16, s17, 3
	v_writelane_b32 v16, s18, 4
	v_writelane_b32 v16, s19, 5
	v_writelane_b32 v16, s20, 6
	v_writelane_b32 v16, s21, 7
	v_writelane_b32 v16, s22, 8
	v_writelane_b32 v16, s23, 9
	v_writelane_b32 v16, s24, 10
	v_writelane_b32 v16, s25, 11
	v_mov_b32_e32 v10, 0x23f08
	ds_read_b32 v11, v10
	s_load_dwordx2 s[14:15], s[0:1], 0xc0
	s_waitcnt lgkmcnt(0)
	v_readfirstlane_b32 s16, v11
	s_cmp_eq_u32 s16, 1
	s_cbranch_scc1 .Llb_go_2
	s_cmp_eq_u32 s16, 2
	s_cbranch_scc1 .Llb_full_2
	s_mov_b64 s[18:19], exec
	s_mov_b64 exec, -1
	s_add_u32 s20, s14, 0x25d04000
	s_addc_u32 s21, s15, 0
	v_and_b32_e32 v2, 63, v234
	v_lshlrev_b32_e32 v3, 2, v2
	v_and_b32_e32 v9, 7, v2
	v_lshlrev_b32_e32 v9, 2, v9
	global_load_dword v4, v3, s[20:21] sc1
	global_load_dword v5, v3, s[20:21] offset:256 sc1
	global_load_dword v6, v3, s[20:21] offset:512 sc1
	global_load_dword v7, v3, s[20:21] offset:768 sc1
	global_load_dword v8, v9, s[20:21] sc1
	s_waitcnt vmcnt(0)
	v_cmp_eq_u32_e32 vcc, v4, v8
	s_mov_b64 s[24:25], vcc
	v_cmp_eq_u32_e32 vcc, v5, v8
	s_and_b64 s[24:25], s[24:25], vcc
	v_cmp_eq_u32_e32 vcc, v6, v8
	s_and_b64 s[24:25], s[24:25], vcc
	v_cmp_eq_u32_e32 vcc, v7, v8
	s_and_b64 s[24:25], s[24:25], vcc
	v_cmp_ne_u32_e32 vcc, 0, v8
	s_and_b64 s[24:25], s[24:25], vcc
	s_mov_b32 s16, 2
	s_cmp_eq_u64 s[24:25], exec
	s_cbranch_scc0 .Llb_dec_2
	s_cmpk_eq_i32 s46, 0x100
	s_cbranch_scc0 .Llb_dec_2
	s_mov_b32 s16, 1

; __device__ __forceinline__ unsigned xb_ld(unsigned* p)              { return __hip_atomic_load(p, __ATOMIC_RELAXED, __HIP_MEMORY_SCOPE_AGENT); }
; __device__ __forceinline__ void xcd_barrier_complete(unsigned* bar, unsigned x, unsigned& nloc, unsigned& nx) {
;     const unsigned G = gridDim.x * gridDim.y * gridDim.z;
;     unsigned sum, cnt, mine, sp = 0u;
;     for (;;) {
;         sum = 0u; cnt = 0u; mine = 0u;
; #pragma unroll
;         for (unsigned j = 0; j < 16; ++j) { const unsigned c = xb_ld(&bar[XB_XCNT(j)]); sum += c; cnt += (c > 0u) ? 1u : 0u; mine = (j == x) ? c : mine; }
;         if (sum == G) break;
;         __builtin_amdgcn_s_sleep(1);
;         if ((++sp & 255u) == 0u) { if (xb_ld(&bar[XB_TMO])) break; if (sp > XB_SPIN_CAP) { atomicAdd(&bar[XB_TMO], 1u); break; } }
;     }
;     nloc = mine > 0u ? mine : 1u; nx = cnt > 0u ? cnt : 1u;
; }
; __device__ __forceinline__ void xcd_barrier(const XcdBarrier& b) {
;     asm volatile("s_waitcnt vmcnt(0)" ::: "memory");
;     __syncthreads();
;     if (threadIdx.x == 0) {
;         unsigned* bar = b.bar;
;         __builtin_amdgcn_s_waitcnt(0);
;         unsigned nloc = b.st[0], nx = b.st[1];
;         if (nloc == 0u) { xcd_barrier_complete(bar, b.x, nloc, nx); b.st[0] = nloc; b.st[1] = nx; }
.Llb_full_2:
	v_readlane_b32 s14, v16, 0
	v_readlane_b32 s15, v16, 1
	v_readlane_b32 s16, v16, 2
	v_readlane_b32 s17, v16, 3
	v_readlane_b32 s18, v16, 4
	v_readlane_b32 s19, v16, 5
	v_readlane_b32 s20, v16, 6
	v_readlane_b32 s21, v16, 7
	v_readlane_b32 s22, v16, 8
	v_readlane_b32 s23, v16, 9
	v_readlane_b32 s24, v16, 10
	v_readlane_b32 s25, v16, 11
	s_nop 4
	s_load_dwordx2 s[8:9], s[0:1], 0xc0
	s_ashr_i32 s11, s10, 31
	s_lshl_b64 s[14:15], s[10:11], 2
	s_waitcnt vmcnt(0) expcnt(0) lgkmcnt(0)
	s_add_u32 s8, s8, s14
	s_addc_u32 s9, s9, s15
	s_add_u32 s8, s8, 0x25d00000
	s_addc_u32 s9, s9, 0
	s_add_i32 s25, s10, 0
	s_add_i32 s25, s25, 0x23f00
	v_mov_b32_e32 v0, s25
	ds_read_b32 v2, v0
	ds_read_b32 v0, v0 offset:4
	s_and_b32 s24, s12, 15
	s_waitcnt lgkmcnt(1)
	v_cmp_ne_u32_e32 vcc, 0, v2
	s_cbranch_vccnz .LBB0_341
	s_add_u32 s10, s8, 0x1000
	s_addc_u32 s11, s9, 0
	s_add_u32 s12, s8, 0x1100
	s_addc_u32 s13, s9, 0
	s_add_u32 s14, s8, 0x1200
	s_addc_u32 s15, s9, 0
	s_mul_i32 s26, s47, s94
	s_add_u32 s16, s8, 0x1300
	s_mul_i32 s26, s26, s46
	s_addc_u32 s17, s9, 0
	s_mov_b32 s27, 1
	v_mov_b32_e32 v16, 0
	s_branch .LBB0_329

; __device__ __forceinline__ unsigned xb_add(unsigned* p, unsigned v) { return __hip_atomic_fetch_add(p, v, __ATOMIC_RELAXED, __HIP_MEMORY_SCOPE_AGENT); }
; __device__ __forceinline__ void xcd_barrier(const XcdBarrier& b) {
;     asm volatile("s_waitcnt vmcnt(0)" ::: "memory");
;     __syncthreads();
;     if (threadIdx.x == 0) {
;         unsigned* bar = b.bar;
;         __builtin_amdgcn_s_waitcnt(0);
;         unsigned nloc = b.st[0], nx = b.st[1];
;         if (nloc == 0u) { xcd_barrier_complete(bar, b.x, nloc, nx); b.st[0] = nloc; b.st[1] = nx; }
;         const unsigned old = xb_add(&bar[XB_XSUB(b.x)], 1u);
.LBB0_423:
	s_mov_b32 s10, 0
	s_getreg_b32 s12, hwreg(HW_REG_XCC_ID, 0, 4)
	s_waitcnt vmcnt(0)
	s_waitcnt lgkmcnt(0)
	s_barrier
	s_and_saveexec_b64 s[6:7], s[4:5]
	s_cbranch_execz .LBB0_475
	v_writelane_b32 v16, s14, 0
	v_writelane_b32 v16, s15, 1
	v_writelane_b32 v16, s16, 2
	v_writelane_b32 v16, s17, 3
	v_writelane_b32 v16, s18, 4
	v_writelane_b32 v16, s19, 5
	v_writelane_b32 v16, s20, 6
	v_writelane_b32 v16, s21, 7
	v_writelane_b32 v16, s22, 8
	v_writelane_b32 v16, s23, 9
	v_writelane_b32 v16, s24, 10
	v_writelane_b32 v16, s25, 11
	v_mov_b32_e32 v10, 0x23f08
	ds_read_b32 v11, v10
	s_load_dwordx2 s[14:15], s[0:1], 0xc0
	s_waitcnt lgkmcnt(0)
	v_readfirstlane_b32 s16, v11
	s_cmp_eq_u32 s16, 1
	s_cbranch_scc1 .Llb_go_3
	s_cmp_eq_u32 s16, 2
	s_cbranch_scc1 .Llb_full_3
	s_mov_b64 s[18:19], exec
	s_mov_b64 exec, -1
	s_add_u32 s20, s14, 0x25d04000
	s_addc_u32 s21, s15, 0
	v_and_b32_e32 v2, 63, v234
	v_lshlrev_b32_e32 v3, 2, v2
	v_and_b32_e32 v9, 7, v2
	v_lshlrev_b32_e32 v9, 2, v9
	global_load_dword v4, v3, s[20:21] sc1
	global_load_dword v5, v3, s[20:21] offset:256 sc1
	global_load_dword v6, v3, s[20:21] offset:512 sc1
	global_load_dword v7, v3, s[20:21] offset:768 sc1
	global_load_dword v8, v9, s[20:21] sc1
	s_waitcnt vmcnt(0)
	v_cmp_eq_u32_e32 vcc, v4, v8
	s_mov_b64 s[24:25], vcc
	v_cmp_eq_u32_e32 vcc, v5, v8
	s_and_b64 s[24:25], s[24:25], vcc
	v_cmp_eq_u32_e32 vcc, v6, v8
	s_and_b64 s[24:25], s[24:25], vcc
	v_cmp_eq_u32_e32 vcc, v7, v8
	s_and_b64 s[24:25], s[24:25], vcc
	v_cmp_ne_u32_e32 vcc, 0, v8
	s_and_b64 s[24:25], s[24:25], vcc
	s_mov_b32 s16, 2
	s_cmp_eq_u64 s[24:25], exec
	s_cbranch_scc0 .Llb_dec_3
	s_cmpk_eq_i32 s46, 0x100
	s_cbranch_scc0 .Llb_dec_3
	s_mov_b32 s16, 1

; __device__ __forceinline__ unsigned xb_ld(unsigned* p)              { return __hip_atomic_load(p, __ATOMIC_RELAXED, __HIP_MEMORY_SCOPE_AGENT); }
; __device__ __forceinline__ void xcd_barrier_complete(unsigned* bar, unsigned x, unsigned& nloc, unsigned& nx) {
;     const unsigned G = gridDim.x * gridDim.y * gridDim.z;
;     unsigned sum, cnt, mine, sp = 0u;
;     for (;;) {
;         sum = 0u; cnt = 0u; mine = 0u;
; #pragma unroll
;         for (unsigned j = 0; j < 16; ++j) { const unsigned c = xb_ld(&bar[XB_XCNT(j)]); sum += c; cnt += (c > 0u) ? 1u : 0u; mine = (j == x) ? c : mine; }
;         if (sum == G) break;
;         __builtin_amdgcn_s_sleep(1);
;         if ((++sp & 255u) == 0u) { if (xb_ld(&bar[XB_TMO])) break; if (sp > XB_SPIN_CAP) { atomicAdd(&bar[XB_TMO], 1u); break; } }
;     }
;     nloc = mine > 0u ? mine : 1u; nx = cnt > 0u ? cnt : 1u;
; }
; __device__ __forceinline__ void xcd_barrier(const XcdBarrier& b) {
;     asm volatile("s_waitcnt vmcnt(0)" ::: "memory");
;     __syncthreads();
;     if (threadIdx.x == 0) {
;         unsigned* bar = b.bar;
;         __builtin_amdgcn_s_waitcnt(0);
;         unsigned nloc = b.st[0], nx = b.st[1];
;         if (nloc == 0u) { xcd_barrier_complete(bar, b.x, nloc, nx); b.st[0] = nloc; b.st[1] = nx; }
.Llb_full_3:
	v_readlane_b32 s14, v16, 0
	v_readlane_b32 s15, v16, 1
	v_readlane_b32 s16, v16, 2
	v_readlane_b32 s17, v16, 3
	v_readlane_b32 s18, v16, 4
	v_readlane_b32 s19, v16, 5
	v_readlane_b32 s20, v16, 6
	v_readlane_b32 s21, v16, 7
	v_readlane_b32 s22, v16, 8
	v_readlane_b32 s23, v16, 9
	v_readlane_b32 s24, v16, 10
	v_readlane_b32 s25, v16, 11
	s_nop 4
	s_ashr_i32 s11, s10, 31
	s_lshl_b64 s[8:9], s[10:11], 2
	s_add_u32 s8, s16, s8
	s_addc_u32 s9, s17, s9
	s_add_u32 s8, s8, 0x25d00000
	s_addc_u32 s9, s9, 0
	s_add_i32 s25, s10, 0
	s_add_i32 s25, s25, 0x23f00
	v_mov_b32_e32 v0, s25
	s_waitcnt vmcnt(0) expcnt(0) lgkmcnt(0)
	ds_read_b32 v2, v0
	ds_read_b32 v0, v0 offset:4
	s_and_b32 s24, s12, 15
	s_waitcnt lgkmcnt(1)
	v_cmp_ne_u32_e32 vcc, 0, v2
	s_cbranch_vccnz .LBB0_439
	s_add_u32 s10, s8, 0x1000
	s_addc_u32 s11, s9, 0
	s_add_u32 s12, s8, 0x1100
	s_addc_u32 s13, s9, 0
	s_add_u32 s14, s8, 0x1200
	s_addc_u32 s15, s9, 0
	s_mul_i32 s26, s47, s94
	s_add_u32 s16, s8, 0x1300
	s_mul_i32 s26, s26, s46
	s_addc_u32 s17, s9, 0
	s_mov_b32 s27, 1
	v_mov_b32_e32 v16, 0
	s_branch .LBB0_427

; __device__ __forceinline__ unsigned xb_add(unsigned* p, unsigned v) { return __hip_atomic_fetch_add(p, v, __ATOMIC_RELAXED, __HIP_MEMORY_SCOPE_AGENT); }
; __device__ __forceinline__ void xcd_barrier(const XcdBarrier& b) {
;     asm volatile("s_waitcnt vmcnt(0)" ::: "memory");
;     __syncthreads();
;     if (threadIdx.x == 0) {
;         unsigned* bar = b.bar;
;         __builtin_amdgcn_s_waitcnt(0);
;         unsigned nloc = b.st[0], nx = b.st[1];
;         if (nloc == 0u) { xcd_barrier_complete(bar, b.x, nloc, nx); b.st[0] = nloc; b.st[1] = nx; }
;         const unsigned old = xb_add(&bar[XB_XSUB(b.x)], 1u);
.LBB0_605:
	s_or_b64 exec, exec, s[8:9]
	s_mov_b32 s6, 0
	s_getreg_b32 s8, hwreg(HW_REG_XCC_ID, 0, 4)
	s_waitcnt vmcnt(0)
	s_barrier
	s_and_saveexec_b64 s[40:41], s[4:5]
	s_cbranch_execz .LBB0_649
	v_writelane_b32 v16, s14, 0
	v_writelane_b32 v16, s15, 1
	v_writelane_b32 v16, s16, 2
	v_writelane_b32 v16, s17, 3
	v_writelane_b32 v16, s18, 4
	v_writelane_b32 v16, s19, 5
	v_writelane_b32 v16, s20, 6
	v_writelane_b32 v16, s21, 7
	v_writelane_b32 v16, s22, 8
	v_writelane_b32 v16, s23, 9
	v_writelane_b32 v16, s24, 10
	v_writelane_b32 v16, s25, 11
	v_mov_b32_e32 v10, 0x23f08
	ds_read_b32 v11, v10
	s_load_dwordx2 s[14:15], s[0:1], 0xc0
	s_waitcnt lgkmcnt(0)
	v_readfirstlane_b32 s16, v11
	s_cmp_eq_u32 s16, 1
	s_cbranch_scc1 .Llb_go_4
	s_cmp_eq_u32 s16, 2
	s_cbranch_scc1 .Llb_full_4
	s_mov_b64 s[18:19], exec
	s_mov_b64 exec, -1
	s_add_u32 s20, s14, 0x25d04000
	s_addc_u32 s21, s15, 0
	v_and_b32_e32 v2, 63, v234
	v_lshlrev_b32_e32 v3, 2, v2
	v_and_b32_e32 v9, 7, v2
	v_lshlrev_b32_e32 v9, 2, v9
	global_load_dword v4, v3, s[20:21] sc1
	global_load_dword v5, v3, s[20:21] offset:256 sc1
	global_load_dword v6, v3, s[20:21] offset:512 sc1
	global_load_dword v7, v3, s[20:21] offset:768 sc1
	global_load_dword v8, v9, s[20:21] sc1
	s_waitcnt vmcnt(0)
	v_cmp_eq_u32_e32 vcc, v4, v8
	s_mov_b64 s[24:25], vcc
	v_cmp_eq_u32_e32 vcc, v5, v8
	s_and_b64 s[24:25], s[24:25], vcc
	v_cmp_eq_u32_e32 vcc, v6, v8
	s_and_b64 s[24:25], s[24:25], vcc
	v_cmp_eq_u32_e32 vcc, v7, v8
	s_and_b64 s[24:25], s[24:25], vcc
	v_cmp_ne_u32_e32 vcc, 0, v8
	s_and_b64 s[24:25], s[24:25], vcc
	s_mov_b32 s16, 2
	s_cmp_eq_u64 s[24:25], exec
	s_cbranch_scc0 .Llb_dec_4
	s_cmpk_eq_i32 s46, 0x100
	s_cbranch_scc0 .Llb_dec_4
	s_mov_b32 s16, 1

; __device__ __forceinline__ unsigned xb_ld(unsigned* p)              { return __hip_atomic_load(p, __ATOMIC_RELAXED, __HIP_MEMORY_SCOPE_AGENT); }
; __device__ __forceinline__ void xcd_barrier_complete(unsigned* bar, unsigned x, unsigned& nloc, unsigned& nx) {
;     const unsigned G = gridDim.x * gridDim.y * gridDim.z;
;     unsigned sum, cnt, mine, sp = 0u;
;     for (;;) {
;         sum = 0u; cnt = 0u; mine = 0u;
; #pragma unroll
;         for (unsigned j = 0; j < 16; ++j) { const unsigned c = xb_ld(&bar[XB_XCNT(j)]); sum += c; cnt += (c > 0u) ? 1u : 0u; mine = (j == x) ? c : mine; }
;         if (sum == G) break;
;         __builtin_amdgcn_s_sleep(1);
;         if ((++sp & 255u) == 0u) { if (xb_ld(&bar[XB_TMO])) break; if (sp > XB_SPIN_CAP) { atomicAdd(&bar[XB_TMO], 1u); break; } }
;     }
;     nloc = mine > 0u ? mine : 1u; nx = cnt > 0u ? cnt : 1u;
; }
; __device__ __forceinline__ void xcd_barrier(const XcdBarrier& b) {
;     asm volatile("s_waitcnt vmcnt(0)" ::: "memory");
;     __syncthreads();
;     if (threadIdx.x == 0) {
;         unsigned* bar = b.bar;
;         __builtin_amdgcn_s_waitcnt(0);
;         unsigned nloc = b.st[0], nx = b.st[1];
;         if (nloc == 0u) { xcd_barrier_complete(bar, b.x, nloc, nx); b.st[0] = nloc; b.st[1] = nx; }
.Llb_full_4:
	v_readlane_b32 s14, v16, 0
	v_readlane_b32 s15, v16, 1
	v_readlane_b32 s16, v16, 2
	v_readlane_b32 s17, v16, 3
	v_readlane_b32 s18, v16, 4
	v_readlane_b32 s19, v16, 5
	v_readlane_b32 s20, v16, 6
	v_readlane_b32 s21, v16, 7
	v_readlane_b32 s22, v16, 8
	v_readlane_b32 s23, v16, 9
	v_readlane_b32 s24, v16, 10
	v_readlane_b32 s25, v16, 11
	s_nop 4
	s_add_i32 s42, s6, 0
	s_add_i32 s42, s42, 0x23f00
	v_mov_b32_e32 v2, s42
	s_waitcnt vmcnt(0) expcnt(0) lgkmcnt(0)
	ds_read_b32 v4, v2
	ds_read_b32 v6, v2 offset:4
	s_ashr_i32 s7, s6, 31
	v_lshl_add_u64 v[0:1], s[6:7], 2, v[0:1]
	s_mov_b64 s[6:7], 0x25d00000
	s_waitcnt lgkmcnt(1)
	v_cmp_ne_u32_e32 vcc, 0, v4
	v_lshl_add_u64 v[0:1], v[0:1], 0, s[6:7]
	s_and_b32 s33, s8, 15
	s_cbranch_vccnz .LBB0_620
	s_mov_b64 s[6:7], 0x1000
	v_lshl_add_u64 v[2:3], v[0:1], 0, s[6:7]
	s_mov_b64 s[6:7], 0x1100
	v_lshl_add_u64 v[4:5], v[0:1], 0, s[6:7]
	s_mov_b64 s[6:7], 0x1200
	s_mul_i32 s24, s47, s94
	s_waitcnt lgkmcnt(0)
	v_lshl_add_u64 v[6:7], v[0:1], 0, s[6:7]
	s_mov_b64 s[6:7], 0x1300
	s_mul_i32 s24, s24, s46
	v_lshl_add_u64 v[8:9], v[0:1], 0, s[6:7]
	s_mov_b32 s25, 1
	s_mov_b64 s[6:7], 0
	s_branch .LBB0_610

; __device__ __forceinline__ unsigned xb_add(unsigned* p, unsigned v) { return __hip_atomic_fetch_add(p, v, __ATOMIC_RELAXED, __HIP_MEMORY_SCOPE_AGENT); }
; __device__ __forceinline__ void xcd_barrier(const XcdBarrier& b) {
;     asm volatile("s_waitcnt vmcnt(0)" ::: "memory");
;     __syncthreads();
;     if (threadIdx.x == 0) {
;         unsigned* bar = b.bar;
;         __builtin_amdgcn_s_waitcnt(0);
;         unsigned nloc = b.st[0], nx = b.st[1];
;         if (nloc == 0u) { xcd_barrier_complete(bar, b.x, nloc, nx); b.st[0] = nloc; b.st[1] = nx; }
;         const unsigned old = xb_add(&bar[XB_XSUB(b.x)], 1u);
.LBB0_1413:
	s_mov_b32 s16, 0
	s_getreg_b32 s10, hwreg(HW_REG_XCC_ID, 0, 4)
	s_waitcnt vmcnt(0)
	s_waitcnt vmcnt(0)
	s_barrier
	s_and_saveexec_b64 s[12:13], s[4:5]
	s_cbranch_execz .LBB0_1465
	v_writelane_b32 v16, s14, 0
	v_writelane_b32 v16, s15, 1
	v_writelane_b32 v16, s16, 2
	v_writelane_b32 v16, s17, 3
	v_writelane_b32 v16, s18, 4
	v_writelane_b32 v16, s19, 5
	v_writelane_b32 v16, s20, 6
	v_writelane_b32 v16, s21, 7
	v_writelane_b32 v16, s22, 8
	v_writelane_b32 v16, s23, 9
	v_writelane_b32 v16, s24, 10
	v_writelane_b32 v16, s25, 11
	v_mov_b32_e32 v10, 0x23f08
	ds_read_b32 v11, v10
	s_load_dwordx2 s[14:15], s[0:1], 0xc0
	s_waitcnt lgkmcnt(0)
	v_readfirstlane_b32 s16, v11
	s_cmp_eq_u32 s16, 1
	s_cbranch_scc1 .Llb_go_11
	s_cmp_eq_u32 s16, 2
	s_cbranch_scc1 .Llb_full_11
	s_mov_b64 s[18:19], exec
	s_mov_b64 exec, -1
	s_add_u32 s20, s14, 0x25d04000
	s_addc_u32 s21, s15, 0
	v_and_b32_e32 v2, 63, v234
	v_lshlrev_b32_e32 v3, 2, v2
	v_and_b32_e32 v9, 7, v2
	v_lshlrev_b32_e32 v9, 2, v9
	global_load_dword v4, v3, s[20:21] sc1
	global_load_dword v5, v3, s[20:21] offset:256 sc1
	global_load_dword v6, v3, s[20:21] offset:512 sc1
	global_load_dword v7, v3, s[20:21] offset:768 sc1
	global_load_dword v8, v9, s[20:21] sc1
	s_waitcnt vmcnt(0)
	v_cmp_eq_u32_e32 vcc, v4, v8
	s_mov_b64 s[24:25], vcc
	v_cmp_eq_u32_e32 vcc, v5, v8
	s_and_b64 s[24:25], s[24:25], vcc
	v_cmp_eq_u32_e32 vcc, v6, v8
	s_and_b64 s[24:25], s[24:25], vcc
	v_cmp_eq_u32_e32 vcc, v7, v8
	s_and_b64 s[24:25], s[24:25], vcc
	v_cmp_ne_u32_e32 vcc, 0, v8
	s_and_b64 s[24:25], s[24:25], vcc
	s_mov_b32 s16, 2
	s_cmp_eq_u64 s[24:25], exec
	s_cbranch_scc0 .Llb_dec_11
	s_cmpk_eq_i32 s46, 0x100
	s_cbranch_scc0 .Llb_dec_11
	s_mov_b32 s16, 1

; __device__ __forceinline__ unsigned xb_add(unsigned* p, unsigned v) { return __hip_atomic_fetch_add(p, v, __ATOMIC_RELAXED, __HIP_MEMORY_SCOPE_AGENT); }
; __device__ __forceinline__ void xcd_barrier(const XcdBarrier& b) {
;     asm volatile("s_waitcnt vmcnt(0)" ::: "memory");
;     __syncthreads();
;     if (threadIdx.x == 0) {
;         unsigned* bar = b.bar;
;         __builtin_amdgcn_s_waitcnt(0);
;         unsigned nloc = b.st[0], nx = b.st[1];
;         if (nloc == 0u) { xcd_barrier_complete(bar, b.x, nloc, nx); b.st[0] = nloc; b.st[1] = nx; }
;         const unsigned old = xb_add(&bar[XB_XSUB(b.x)], 1u);
.LBB0_1510:
	s_load_dwordx2 s[24:25], s[0:1], 0xc0
	s_load_dword s94, s[0:1], 0xd0
.LBB0_1511:
	s_mov_b32 s16, 0
	s_getreg_b32 s10, hwreg(HW_REG_XCC_ID, 0, 4)
	s_waitcnt vmcnt(0)
	s_waitcnt lgkmcnt(0)
	s_barrier
	s_and_saveexec_b64 s[12:13], s[4:5]
	s_cbranch_execz .LBB0_1563
	v_writelane_b32 v16, s14, 0
	v_writelane_b32 v16, s15, 1
	v_writelane_b32 v16, s16, 2
	v_writelane_b32 v16, s17, 3
	v_writelane_b32 v16, s18, 4
	v_writelane_b32 v16, s19, 5
	v_writelane_b32 v16, s20, 6
	v_writelane_b32 v16, s21, 7
	v_writelane_b32 v16, s22, 8
	v_writelane_b32 v16, s23, 9
	v_writelane_b32 v16, s24, 10
	v_writelane_b32 v16, s25, 11
	v_mov_b32_e32 v10, 0x23f08
	ds_read_b32 v11, v10
	s_load_dwordx2 s[14:15], s[0:1], 0xc0
	s_waitcnt lgkmcnt(0)
	v_readfirstlane_b32 s16, v11
	s_cmp_eq_u32 s16, 1
	s_cbranch_scc1 .Llb_go_12
	s_cmp_eq_u32 s16, 2
	s_cbranch_scc1 .Llb_full_12
	s_mov_b64 s[18:19], exec
	s_mov_b64 exec, -1
	s_add_u32 s20, s14, 0x25d04000
	s_addc_u32 s21, s15, 0
	v_and_b32_e32 v2, 63, v234
	v_lshlrev_b32_e32 v3, 2, v2
	v_and_b32_e32 v9, 7, v2
	v_lshlrev_b32_e32 v9, 2, v9
	global_load_dword v4, v3, s[20:21] sc1
	global_load_dword v5, v3, s[20:21] offset:256 sc1
	global_load_dword v6, v3, s[20:21] offset:512 sc1
	global_load_dword v7, v3, s[20:21] offset:768 sc1
	global_load_dword v8, v9, s[20:21] sc1
	s_waitcnt vmcnt(0)
	v_cmp_eq_u32_e32 vcc, v4, v8
	s_mov_b64 s[24:25], vcc
	v_cmp_eq_u32_e32 vcc, v5, v8
	s_and_b64 s[24:25], s[24:25], vcc
	v_cmp_eq_u32_e32 vcc, v6, v8
	s_and_b64 s[24:25], s[24:25], vcc
	v_cmp_eq_u32_e32 vcc, v7, v8
	s_and_b64 s[24:25], s[24:25], vcc
	v_cmp_ne_u32_e32 vcc, 0, v8
	s_and_b64 s[24:25], s[24:25], vcc
	s_mov_b32 s16, 2
	s_cmp_eq_u64 s[24:25], exec
	s_cbranch_scc0 .Llb_dec_12
	s_cmpk_eq_i32 s46, 0x100
	s_cbranch_scc0 .Llb_dec_12
	s_mov_b32 s16, 1

; __device__ __forceinline__ unsigned xb_ld(unsigned* p)              { return __hip_atomic_load(p, __ATOMIC_RELAXED, __HIP_MEMORY_SCOPE_AGENT); }
; __device__ __forceinline__ void xcd_barrier_complete(unsigned* bar, unsigned x, unsigned& nloc, unsigned& nx) {
;     const unsigned G = gridDim.x * gridDim.y * gridDim.z;
;     unsigned sum, cnt, mine, sp = 0u;
;     for (;;) {
;         sum = 0u; cnt = 0u; mine = 0u;
; #pragma unroll
;         for (unsigned j = 0; j < 16; ++j) { const unsigned c = xb_ld(&bar[XB_XCNT(j)]); sum += c; cnt += (c > 0u) ? 1u : 0u; mine = (j == x) ? c : mine; }
;         if (sum == G) break;
;         __builtin_amdgcn_s_sleep(1);
;         if ((++sp & 255u) == 0u) { if (xb_ld(&bar[XB_TMO])) break; if (sp > XB_SPIN_CAP) { atomicAdd(&bar[XB_TMO], 1u); break; } }
;     }
;     nloc = mine > 0u ? mine : 1u; nx = cnt > 0u ? cnt : 1u;
; }
; __device__ __forceinline__ void xcd_barrier(const XcdBarrier& b) {
;     asm volatile("s_waitcnt vmcnt(0)" ::: "memory");
;     __syncthreads();
;     if (threadIdx.x == 0) {
;         unsigned* bar = b.bar;
;         __builtin_amdgcn_s_waitcnt(0);
;         unsigned nloc = b.st[0], nx = b.st[1];
;         if (nloc == 0u) { xcd_barrier_complete(bar, b.x, nloc, nx); b.st[0] = nloc; b.st[1] = nx; }
.Llb_full_12:
	v_readlane_b32 s14, v16, 0
	v_readlane_b32 s15, v16, 1
	v_readlane_b32 s16, v16, 2
	v_readlane_b32 s17, v16, 3
	v_readlane_b32 s18, v16, 4
	v_readlane_b32 s19, v16, 5
	v_readlane_b32 s20, v16, 6
	v_readlane_b32 s21, v16, 7
	v_readlane_b32 s22, v16, 8
	v_readlane_b32 s23, v16, 9
	v_readlane_b32 s24, v16, 10
	v_readlane_b32 s25, v16, 11
	s_nop 4
	s_ashr_i32 s17, s16, 31
	s_lshl_b64 s[14:15], s[16:17], 2
	s_add_u32 s11, s24, s14
	s_addc_u32 s15, s25, s15
	s_add_u32 s14, s11, 0x25d00000
	s_addc_u32 s15, s15, 0
	s_add_i32 s11, s16, 0
	s_add_i32 s11, s11, 0x23f00
	v_mov_b32_e32 v0, s11
	s_waitcnt vmcnt(0) expcnt(0) lgkmcnt(0)
	ds_read_b32 v2, v0
	ds_read_b32 v0, v0 offset:4
	s_and_b32 s10, s10, 15
	s_waitcnt lgkmcnt(1)
	v_cmp_ne_u32_e32 vcc, 0, v2
	s_cbranch_vccnz .LBB0_1527
	s_add_u32 s16, s14, 0x1000
	s_addc_u32 s17, s15, 0
	s_add_u32 s18, s14, 0x1100
	s_addc_u32 s19, s15, 0
	s_add_u32 s20, s14, 0x1200
	s_addc_u32 s21, s15, 0
	s_mul_i32 s30, s47, s94
	s_add_u32 s22, s14, 0x1300
	s_mul_i32 s30, s30, s46
	s_addc_u32 s23, s15, 0
	s_mov_b32 s31, 1
	v_mov_b32_e32 v16, 0
	s_branch .LBB0_1515

; __device__ __forceinline__ unsigned xb_add(unsigned* p, unsigned v) { return __hip_atomic_fetch_add(p, v, __ATOMIC_RELAXED, __HIP_MEMORY_SCOPE_AGENT); }
; __device__ __forceinline__ void xcd_barrier(const XcdBarrier& b) {
;     asm volatile("s_waitcnt vmcnt(0)" ::: "memory");
;     __syncthreads();
;     if (threadIdx.x == 0) {
;         unsigned* bar = b.bar;
;         __builtin_amdgcn_s_waitcnt(0);
;         unsigned nloc = b.st[0], nx = b.st[1];
;         if (nloc == 0u) { xcd_barrier_complete(bar, b.x, nloc, nx); b.st[0] = nloc; b.st[1] = nx; }
;         const unsigned old = xb_add(&bar[XB_XSUB(b.x)], 1u);
.LBB0_1693:
	s_or_b64 exec, exec, s[14:15]
	s_mov_b32 s12, 0
	s_getreg_b32 s10, hwreg(HW_REG_XCC_ID, 0, 4)
	s_waitcnt vmcnt(0)
	s_barrier
	s_and_saveexec_b64 s[48:49], s[4:5]
	s_cbranch_execz .LBB0_1737
	v_writelane_b32 v16, s14, 0
	v_writelane_b32 v16, s15, 1
	v_writelane_b32 v16, s16, 2
	v_writelane_b32 v16, s17, 3
	v_writelane_b32 v16, s18, 4
	v_writelane_b32 v16, s19, 5
	v_writelane_b32 v16, s20, 6
	v_writelane_b32 v16, s21, 7
	v_writelane_b32 v16, s22, 8
	v_writelane_b32 v16, s23, 9
	v_writelane_b32 v16, s24, 10
	v_writelane_b32 v16, s25, 11
	v_mov_b32_e32 v10, 0x23f08
	ds_read_b32 v11, v10
	s_load_dwordx2 s[14:15], s[0:1], 0xc0
	s_waitcnt lgkmcnt(0)
	v_readfirstlane_b32 s16, v11
	s_cmp_eq_u32 s16, 1
	s_cbranch_scc1 .Llb_go_13
	s_cmp_eq_u32 s16, 2
	s_cbranch_scc1 .Llb_full_13
	s_mov_b64 s[18:19], exec
	s_mov_b64 exec, -1
	s_add_u32 s20, s14, 0x25d04000
	s_addc_u32 s21, s15, 0
	v_and_b32_e32 v2, 63, v234
	v_lshlrev_b32_e32 v3, 2, v2
	v_and_b32_e32 v9, 7, v2
	v_lshlrev_b32_e32 v9, 2, v9
	global_load_dword v4, v3, s[20:21] sc1
	global_load_dword v5, v3, s[20:21] offset:256 sc1
	global_load_dword v6, v3, s[20:21] offset:512 sc1
	global_load_dword v7, v3, s[20:21] offset:768 sc1
	global_load_dword v8, v9, s[20:21] sc1
	s_waitcnt vmcnt(0)
	v_cmp_eq_u32_e32 vcc, v4, v8
	s_mov_b64 s[24:25], vcc
	v_cmp_eq_u32_e32 vcc, v5, v8
	s_and_b64 s[24:25], s[24:25], vcc
	v_cmp_eq_u32_e32 vcc, v6, v8
	s_and_b64 s[24:25], s[24:25], vcc
	v_cmp_eq_u32_e32 vcc, v7, v8
	s_and_b64 s[24:25], s[24:25], vcc
	v_cmp_ne_u32_e32 vcc, 0, v8
	s_and_b64 s[24:25], s[24:25], vcc
	s_mov_b32 s16, 2
	s_cmp_eq_u64 s[24:25], exec
	s_cbranch_scc0 .Llb_dec_13
	s_cmpk_eq_i32 s46, 0x100
	s_cbranch_scc0 .Llb_dec_13
	s_mov_b32 s16, 1
